# norm_rows chunk waits and the hgC steady-state top-of-chunk waits now count the stores/loads issued after the awaited ops (in-order vmcnt) instead of draining them; hgC first iteration keeps the origi
# speedup vs baseline: 1.0070x; 1.0044x over previous
; DI void norm_rows(const float* X, const float* gain, const float* sh, const float* sc, bf16_t* H, int gw, int ngw, int lane) {
;     for (int m = gw; m < T_TOK; m += ngw) {
;         const int b = m >> 12;
;         const f32x4* xr = (const f32x4*)(X + (size_t)m * DM) + lane;
;         f32x4 v[8]; float s = 0.f;
; #pragma unroll
;         for (int j = 0; j < 8; ++j) { v[j] = xr[64 * j]; s += (v[j].x * v[j].x + v[j].y * v[j].y) + (v[j].z * v[j].z + v[j].w * v[j].w); }
;         const float rstd = rsqrtf(wave_sum(s) * (1.f / DM) + EPS);
.LBB0_158:
	global_load_dwordx4 v[28:31], v[46:47], off offset:-4096
	global_load_dwordx4 v[24:27], v[46:47], off offset:-3072
	global_load_dwordx4 v[20:23], v[46:47], off offset:-2048
	global_load_dwordx4 v[4:7], v[46:47], off offset:1024
	global_load_dwordx4 v[12:15], v[46:47], off offset:-1024
	global_load_dwordx4 v[16:19], v[46:47], off
	global_load_dwordx4 v[8:11], v[46:47], off offset:2048
	global_load_dwordx4 v[0:3], v[46:47], off offset:3072
	global_load_dwordx4 v[58:61], v[32:33], off
	s_ashr_i32 s12, s4, 12
	v_mad_i64_i32 v[70:71], s[10:11], s12, v57, v[34:35]
	v_mad_i64_i32 v[72:73], s[10:11], s12, v57, v[36:37]
	global_load_dwordx4 v[62:65], v[70:71], off
	global_load_dwordx4 v[66:69], v[72:73], off
	v_lshl_add_u64 v[108:109], v[70:71], 0, s[98:99]
	v_lshl_add_u64 v[110:111], v[72:73], 0, s[98:99]
	global_load_dwordx4 v[112:115], v[32:33], off offset:1024
	global_load_dwordx4 v[116:119], v[70:71], off offset:1024
	global_load_dwordx4 v[120:123], v[72:73], off offset:1024
	global_load_dwordx4 v[124:127], v[32:33], off offset:2048
	global_load_dwordx4 v[128:131], v[70:71], off offset:2048
	global_load_dwordx4 v[132:135], v[72:73], off offset:2048
	global_load_dwordx4 v[136:139], v[32:33], off offset:3072
	global_load_dwordx4 v[140:143], v[70:71], off offset:3072
	global_load_dwordx4 v[148:151], v[72:73], off offset:3072
	global_load_dwordx4 v[152:155], v[38:39], off
	global_load_dwordx4 v[156:159], v[108:109], off
	global_load_dwordx4 v[160:163], v[110:111], off
	global_load_dwordx4 v[164:167], v[40:41], off
	global_load_dwordx4 v[168:171], v[108:109], off offset:1024
	global_load_dwordx4 v[172:175], v[110:111], off offset:1024
	global_load_dwordx4 v[176:179], v[42:43], off
	global_load_dwordx4 v[180:183], v[108:109], off offset:2048
	global_load_dwordx4 v[184:187], v[110:111], off offset:2048
	global_load_dwordx4 v[188:191], v[44:45], off
	global_load_dwordx4 v[192:195], v[108:109], off offset:3072
	global_load_dwordx4 v[196:199], v[110:111], off offset:3072
	s_add_i32 s4, s4, s84
	v_lshl_add_u64 v[46:47], v[46:47], 0, s[6:7]
	s_cmpk_lt_i32 s4, 0x4000
	s_waitcnt vmcnt(31)
	v_mov_b32_e32 v76, v29
	s_waitcnt vmcnt(30)
	v_mov_b32_e32 v77, v25
	s_waitcnt vmcnt(29)
	v_pk_mul_f32 v[78:79], v[22:23], v[22:23]
	v_pk_mul_f32 v[80:81], v[20:21], v[20:21]
	s_waitcnt vmcnt(28)
	v_pk_mul_f32 v[82:83], v[6:7], v[6:7]
	v_pk_mul_f32 v[84:85], v[4:5], v[4:5]
	v_mov_b32_e32 v88, v31
	v_mov_b32_e32 v89, v27
	v_mov_b32_e32 v74, v28
	v_mov_b32_e32 v75, v24
	v_mov_b32_e32 v86, v30
	v_mov_b32_e32 v87, v26
	v_pk_mov_b32 v[98:99], v[80:81], v[78:79] op_sel:[1,0]
	v_mov_b32_e32 v81, v79
	v_pk_mov_b32 v[78:79], v[84:85], v[82:83] op_sel:[1,0]
	v_mov_b32_e32 v85, v83
	v_pk_mul_f32 v[76:77], v[76:77], v[76:77]
	v_pk_mul_f32 v[82:83], v[88:89], v[88:89]
	v_pk_fma_f32 v[74:75], v[74:75], v[74:75], v[76:77]
	v_pk_fma_f32 v[76:77], v[86:87], v[86:87], v[82:83]
	s_waitcnt vmcnt(27)
	v_mul_f32_e32 v90, v13, v13
	v_mul_f32_e32 v92, v15, v15
	v_pk_add_f32 v[80:81], v[98:99], v[80:81]
	v_pk_add_f32 v[74:75], v[74:75], v[76:77]
	s_waitcnt vmcnt(26)
	v_mul_f32_e32 v97, v18, v18
	v_mul_f32_e32 v100, v19, v19
	v_mul_f32_e32 v103, v17, v17
	v_mul_f32_e32 v104, v16, v16
	v_pk_fma_f32 v[88:89], v[12:13], v[12:13], v[90:91] op_sel_hi:[1,1,0]
	v_pk_fma_f32 v[90:91], v[14:15], v[14:15], v[92:93] op_sel_hi:[1,1,0]
	v_pk_add_f32 v[80:81], v[80:81], v[80:81] op_sel:[0,1] op_sel_hi:[1,0]
	v_pk_add_f32 v[74:75], v[74:75], v[74:75] op_sel:[0,1] op_sel_hi:[1,0]
	v_mov_b32_e32 v89, v97
	v_mov_b32_e32 v91, v100
	v_mov_b32_e32 v81, v103
	v_mov_b32_e32 v75, v104
	v_pk_add_f32 v[76:77], v[88:89], v[90:91]
	v_pk_add_f32 v[74:75], v[74:75], v[80:81]
	s_waitcnt vmcnt(25)
	v_mul_f32_e32 v94, v9, v9
	v_mul_f32_e32 v96, v11, v11
	v_pk_add_f32 v[78:79], v[78:79], v[84:85]
	v_pk_add_f32 v[74:75], v[74:75], v[76:77]
	s_waitcnt vmcnt(24)
	v_mul_f32_e32 v101, v2, v2
	v_mul_f32_e32 v102, v3, v3
	v_mul_f32_e32 v105, v1, v1
	v_mul_f32_e32 v106, v0, v0
	v_pk_fma_f32 v[92:93], v[8:9], v[8:9], v[94:95] op_sel_hi:[1,1,0]
	v_pk_fma_f32 v[94:95], v[10:11], v[10:11], v[96:97] op_sel_hi:[1,1,0]
	v_pk_add_f32 v[78:79], v[78:79], v[78:79] op_sel:[0,1] op_sel_hi:[1,0]
	v_pk_add_f32 v[74:75], v[74:75], v[74:75] op_sel:[0,1] op_sel_hi:[1,0]
	v_mov_b32_e32 v93, v101
	v_mov_b32_e32 v95, v102
	v_mov_b32_e32 v79, v105
	v_mov_b32_e32 v75, v106
	v_pk_add_f32 v[82:83], v[92:93], v[94:95]
	v_pk_add_f32 v[74:75], v[74:75], v[78:79]
	s_waitcnt vmcnt(22)
	v_pk_add_f32 v[64:65], v[64:65], 1.0 op_sel_hi:[1,0]
	v_pk_add_f32 v[74:75], v[74:75], v[82:83]
	v_pk_add_f32 v[62:63], v[62:63], 1.0 op_sel_hi:[1,0]
	v_add_f32_e32 v74, v74, v75
	s_waitcnt lgkmcnt(0)
	s_nop 1
	v_add_f32_dpp v74, v74, v74 quad_perm:[1,0,3,2] row_mask:0xf bank_mask:0xf
	s_waitcnt lgkmcnt(0)
	s_nop 1
	v_add_f32_dpp v74, v74, v74 quad_perm:[2,3,0,1] row_mask:0xf bank_mask:0xf
	s_waitcnt lgkmcnt(0)
	s_nop 1
	v_add_f32_dpp v74, v74, v74 row_half_mirror row_mask:0xf bank_mask:0xf
	s_waitcnt lgkmcnt(0)
	s_nop 1
	v_add_f32_dpp v74, v74, v74 row_mirror row_mask:0xf bank_mask:0xf
	ds_bpermute_b32 v75, v54, v74
	s_waitcnt lgkmcnt(0)
	v_add_f32_e32 v74, v74, v75
	ds_bpermute_b32 v75, v55, v74
	s_waitcnt lgkmcnt(0)
; DI unsigned pk2(float lo, float hi) { return pg8::cvt_pk_bf16(lo, hi); }
; DI void norm_rows(const float* X, const float* gain, const float* sh, const float* sc, bf16_t* H, int gw, int ngw, int lane) {
;     ...
;         const float rstd = rsqrtf(wave_sum(s) * (1.f / DM) + EPS);
;         const f32x4* gp = (const f32x4*)gain + lane; const f32x4* scp = (const f32x4*)(sc + (size_t)b * MODW) + lane; const f32x4* shp = (const f32x4*)(sh + (size_t)b * MODW) + lane;
;         u32x2* o = (u32x2*)(H + (size_t)m * DM) + lane;
; #pragma unroll
;         for (int j = 0; j < 8; ++j) { const f32x4 r = v[j] * rstd * gp[64 * j] * (scp[64 * j] + 1.0f) + shp[64 * j]; u32x2 w; w.x = pk2(r.x, r.y); w.y = pk2(r.z, r.w); o[64 * j] = w; }
	v_add_f32_e32 v74, v74, v75
	v_fmamk_f32 v74, v74, 0x3a000000, v56
	v_mul_f32_e32 v75, 0x4b800000, v74
	v_cmp_gt_f32_e32 vcc, s3, v74
	s_nop 1
	v_cndmask_b32_e32 v74, v74, v75, vcc
	v_rsq_f32_e32 v74, v74
	s_nop 0
	v_mul_f32_e32 v75, 0x45800000, v74
	v_cndmask_b32_e32 v74, v74, v75, vcc
	v_pk_mul_f32 v[30:31], v[30:31], v[74:75] op_sel_hi:[1,0]
	v_pk_mul_f32 v[28:29], v[28:29], v[74:75] op_sel_hi:[1,0]
	v_pk_mul_f32 v[30:31], v[60:61], v[30:31]
	v_pk_mul_f32 v[28:29], v[58:59], v[28:29]
	s_waitcnt vmcnt(21)
	v_pk_fma_f32 v[30:31], v[64:65], v[30:31], v[68:69]
	v_pk_fma_f32 v[28:29], v[62:63], v[28:29], v[66:67]
	v_pk_mul_f32 v[26:27], v[26:27], v[74:75] op_sel_hi:[1,0]
	v_cvt_pk_bf16_f32 v28, v28, v29
	v_cvt_pk_bf16_f32 v29, v30, v31
	global_store_dwordx2 v[48:49], v[28:29], off
	v_pk_mul_f32 v[24:25], v[24:25], v[74:75] op_sel_hi:[1,0]
	v_pk_mul_f32 v[22:23], v[22:23], v[74:75] op_sel_hi:[1,0]
	v_pk_mul_f32 v[20:21], v[20:21], v[74:75] op_sel_hi:[1,0]
	v_pk_mul_f32 v[14:15], v[14:15], v[74:75] op_sel_hi:[1,0]
	v_pk_mul_f32 v[12:13], v[12:13], v[74:75] op_sel_hi:[1,0]
	v_pk_mul_f32 v[18:19], v[18:19], v[74:75] op_sel_hi:[1,0]
	v_pk_mul_f32 v[16:17], v[16:17], v[74:75] op_sel_hi:[1,0]
	v_pk_mul_f32 v[6:7], v[6:7], v[74:75] op_sel_hi:[1,0]
	v_pk_mul_f32 v[4:5], v[4:5], v[74:75] op_sel_hi:[1,0]
	v_pk_mul_f32 v[10:11], v[10:11], v[74:75] op_sel_hi:[1,0]
	v_pk_mul_f32 v[8:9], v[8:9], v[74:75] op_sel_hi:[1,0]
	v_pk_mul_f32 v[2:3], v[2:3], v[74:75] op_sel_hi:[1,0]
	v_pk_mul_f32 v[0:1], v[0:1], v[74:75] op_sel_hi:[1,0]
	s_waitcnt vmcnt(21)
	v_pk_mul_f32 v[24:25], v[112:113], v[24:25]
	v_pk_mul_f32 v[26:27], v[114:115], v[26:27]
	s_waitcnt vmcnt(20)
	v_pk_add_f32 v[28:29], v[118:119], 1.0 op_sel_hi:[1,0]
	v_pk_add_f32 v[30:31], v[116:117], 1.0 op_sel_hi:[1,0]
	s_waitcnt vmcnt(19)
	v_pk_fma_f32 v[26:27], v[28:29], v[26:27], v[122:123]
	v_pk_fma_f32 v[24:25], v[30:31], v[24:25], v[120:121]
	s_nop 0
	v_cvt_pk_bf16_f32 v24, v24, v25
	v_cvt_pk_bf16_f32 v25, v26, v27
	global_store_dwordx2 v[48:49], v[24:25], off offset:512
	s_waitcnt vmcnt(19)
	v_pk_mul_f32 v[20:21], v[124:125], v[20:21]
	v_pk_mul_f32 v[22:23], v[126:127], v[22:23]
	s_waitcnt vmcnt(18)
	v_pk_add_f32 v[24:25], v[130:131], 1.0 op_sel_hi:[1,0]
	v_pk_add_f32 v[26:27], v[128:129], 1.0 op_sel_hi:[1,0]
	s_waitcnt vmcnt(17)
	v_pk_fma_f32 v[22:23], v[24:25], v[22:23], v[134:135]
	v_pk_fma_f32 v[20:21], v[26:27], v[20:21], v[132:133]
	v_add_co_u32_e32 v58, vcc, s5, v70
	v_cvt_pk_bf16_f32 v20, v20, v21
	v_cvt_pk_bf16_f32 v21, v22, v23
	global_store_dwordx2 v[48:49], v[20:21], off offset:1024
	v_addc_co_u32_e32 v59, vcc, 0, v71, vcc
	v_add_co_u32_e32 v60, vcc, s5, v72
	s_waitcnt vmcnt(17)
	v_pk_mul_f32 v[12:13], v[136:137], v[12:13]
	v_pk_mul_f32 v[14:15], v[138:139], v[14:15]
	s_waitcnt vmcnt(16)
	v_pk_add_f32 v[20:21], v[142:143], 1.0 op_sel_hi:[1,0]
	v_pk_add_f32 v[22:23], v[140:141], 1.0 op_sel_hi:[1,0]
	s_waitcnt vmcnt(15)
	v_pk_fma_f32 v[14:15], v[20:21], v[14:15], v[150:151]
	v_pk_fma_f32 v[12:13], v[22:23], v[12:13], v[148:149]
	v_addc_co_u32_e32 v61, vcc, 0, v73, vcc
	v_cvt_pk_bf16_f32 v12, v12, v13
	v_cvt_pk_bf16_f32 v13, v14, v15
	global_store_dwordx2 v[48:49], v[12:13], off offset:1536
	s_waitcnt vmcnt(15)
	v_pk_mul_f32 v[12:13], v[16:17], v[152:153]
	v_pk_mul_f32 v[14:15], v[18:19], v[154:155]
	s_waitcnt vmcnt(14)
	v_pk_add_f32 v[16:17], v[158:159], 1.0 op_sel_hi:[1,0]
	v_pk_add_f32 v[18:19], v[156:157], 1.0 op_sel_hi:[1,0]
	s_waitcnt vmcnt(13)
	v_pk_fma_f32 v[14:15], v[14:15], v[16:17], v[162:163]
	v_pk_fma_f32 v[12:13], v[12:13], v[18:19], v[160:161]
	s_nop 0
	v_cvt_pk_bf16_f32 v12, v12, v13
	v_cvt_pk_bf16_f32 v13, v14, v15
	global_store_dwordx2 v[48:49], v[12:13], off offset:2048
	s_waitcnt vmcnt(13)
	v_pk_mul_f32 v[4:5], v[4:5], v[164:165]
	v_pk_mul_f32 v[6:7], v[6:7], v[166:167]
	s_waitcnt vmcnt(12)
	v_pk_add_f32 v[12:13], v[170:171], 1.0 op_sel_hi:[1,0]
	v_pk_add_f32 v[14:15], v[168:169], 1.0 op_sel_hi:[1,0]
	s_waitcnt vmcnt(11)
	v_pk_fma_f32 v[6:7], v[6:7], v[12:13], v[174:175]
	v_pk_fma_f32 v[4:5], v[4:5], v[14:15], v[172:173]
	s_nop 0
	v_cvt_pk_bf16_f32 v4, v4, v5
	v_cvt_pk_bf16_f32 v5, v6, v7
	global_store_dwordx2 v[48:49], v[4:5], off offset:2560
	s_waitcnt vmcnt(11)
	v_pk_mul_f32 v[4:5], v[8:9], v[176:177]
	v_pk_mul_f32 v[6:7], v[10:11], v[178:179]
	s_waitcnt vmcnt(10)
	v_pk_add_f32 v[8:9], v[182:183], 1.0 op_sel_hi:[1,0]
	v_pk_add_f32 v[10:11], v[180:181], 1.0 op_sel_hi:[1,0]
	s_waitcnt vmcnt(9)
	v_pk_fma_f32 v[6:7], v[6:7], v[8:9], v[186:187]
	v_pk_fma_f32 v[4:5], v[4:5], v[10:11], v[184:185]
	s_nop 0
	v_cvt_pk_bf16_f32 v4, v4, v5
	v_cvt_pk_bf16_f32 v5, v6, v7
	global_store_dwordx2 v[48:49], v[4:5], off offset:3072
	s_waitcnt vmcnt(9)
	v_pk_mul_f32 v[0:1], v[0:1], v[188:189]
	v_pk_mul_f32 v[2:3], v[2:3], v[190:191]
	s_waitcnt vmcnt(8)
	v_pk_add_f32 v[4:5], v[194:195], 1.0 op_sel_hi:[1,0]
	v_pk_add_f32 v[6:7], v[192:193], 1.0 op_sel_hi:[1,0]
	s_waitcnt vmcnt(7)
	v_pk_fma_f32 v[2:3], v[2:3], v[4:5], v[198:199]
	v_pk_fma_f32 v[0:1], v[0:1], v[6:7], v[196:197]
	s_nop 0
	v_cvt_pk_bf16_f32 v0, v0, v1
	v_cvt_pk_bf16_f32 v1, v2, v3
	global_store_dwordx2 v[48:49], v[0:1], off offset:3584
	v_lshl_add_u64 v[48:49], v[48:49], 0, s[8:9]
	s_cbranch_scc1 .LBB0_158

; DI void hg_phase_c(const P& p, const bf16_t* PROJ, const bf16_t* ST, bf16_t* Y, LAS unsigned char* L, unsigned* qcnt) {
;     ...
;         if (tid == 0) qs[par ^ 1] = __hip_atomic_fetch_add(qcnt, 1u, __ATOMIC_RELAXED, __HIP_MEMORY_SCOPE_AGENT);
;         __syncthreads();
;         const int nxt = (int)qs[par ^ 1];
;         hg_raw_store(rawf, tid, rf); hg_raw_store(rawv, tid, rv); hg_raw_store(rawq, tid, rq);
;         if (nxt < 2048) { hg_raw_load(PROJ, nxt, 4096, roff, rf); hg_raw_load(PROJ, nxt, 5120, roff, rv); hg_raw_load(PROJ, nxt, 3072, roff, rq); }
.LBB0_424:
	s_xor_b32 s95, s95, 1
	s_and_saveexec_b64 s[50:51], s[4:5]
	s_cbranch_execz .LBB0_428
	s_lshl_b32 s62, s95, 2
	s_add_i32 s62, s62, 0
	s_add_i32 s62, s62, 0x220a0
	s_waitcnt vmcnt(4)
	v_mov_b32_e32 v1, s62
	ds_write_b32 v1, v213
.LBB0_428:
	s_or_b64 exec, exec, s[50:51]
	s_lshl_b32 s50, s95, 2
	s_add_i32 s50, s50, 0
	s_add_i32 s50, s50, 0x220a0
	v_mov_b32_e32 v0, s50
	s_waitcnt lgkmcnt(0)
	s_barrier
	ds_read_b32 v0, v0
	s_waitcnt vmcnt(25)
	ds_write_b128 v173, v[48:51]
	s_waitcnt vmcnt(23)
	ds_write_b128 v173, v[56:59] offset:8704
	ds_write_b128 v181, v[52:55]
	s_waitcnt vmcnt(22)
	ds_write_b128 v181, v[60:63] offset:8704
	s_waitcnt vmcnt(21)
	ds_write_b128 v182, v[64:67]
	s_waitcnt vmcnt(20)
	ds_write_b128 v182, v[68:71] offset:8704
	s_branch .Lhgc_join

; DI void hg_phase_c(const P& p, const bf16_t* PROJ, const bf16_t* ST, bf16_t* Y, LAS unsigned char* L, unsigned* qcnt) {
;     ...
;         const int nxt = (int)qs[par ^ 1];
;         hg_raw_store(rawf, tid, rf); hg_raw_store(rawv, tid, rv); hg_raw_store(rawq, tid, rq);
;         if (nxt < 2048) { hg_raw_load(PROJ, nxt, 4096, roff, rf); hg_raw_load(PROJ, nxt, 5120, roff, rv); hg_raw_load(PROJ, nxt, 3072, roff, rq); }
.Lhgc_join:
	s_waitcnt lgkmcnt(6)
	v_cmp_lt_i32_e64 s[50:51], s85, v0
	v_readfirstlane_b32 s96, v0
	s_and_b64 vcc, exec, s[50:51]
	s_lshl_b32 s62, s76, 1
	s_and_b32 s62, s62, 0x380
	v_or_b32_e32 v212, s62, v172
	v_lshlrev_b32_e32 v212, 2, v212
	s_add_u32 s100, s52, 0x1000
	s_addc_u32 s101, s53, 0
	global_load_dword v210, v212, s[52:53]
	global_load_dword v211, v212, s[100:101]
	s_cbranch_vccnz .Lhgc_nopf
	s_ashr_i32 s78, s96, 9
	s_ashr_i32 s79, s78, 31
	s_lshl_b32 s62, s96, 6
	s_lshl_b64 s[78:79], s[78:79], 12
	s_and_b32 s62, s62, 0xfc0
	s_or_b32 s62, s78, s62
	s_mul_i32 s77, s79, 0x3800
	s_mul_hi_u32 s78, s62, 0x3800
	s_add_i32 s78, s78, s77
	s_mulk_i32 s62, 0x3800
	s_add_u32 s62, s64, s62
	s_addc_u32 s77, s65, s78
	s_lshl_b32 s78, s96, 2
	s_and_b32 s78, s78, 0x700
	s_add_u32 s78, s62, s78
	s_addc_u32 s79, s77, 0
	v_lshl_add_u64 v[0:1], v[152:153], 1, s[78:79]
	v_add_co_u32_e32 v2, vcc, s89, v0
	s_nop 1
	v_addc_co_u32_e32 v3, vcc, 0, v1, vcc
	v_add_co_u32_e32 v4, vcc, 0x72000, v0
	s_nop 1
	v_addc_co_u32_e32 v5, vcc, 0, v1, vcc
	global_load_dwordx4 v[48:51], v[2:3], off
	global_load_dwordx4 v[52:55], v[2:3], off offset:2048
	global_load_dwordx4 v[56:59], v[4:5], off
	global_load_dwordx4 v[60:63], v[4:5], off offset:2048
	v_add_co_u32_e32 v2, vcc, 0x1000, v0
	s_nop 1
	v_addc_co_u32_e32 v3, vcc, 0, v1, vcc
	v_add_co_u32_e32 v0, vcc, 0x71000, v0
	s_nop 1
	v_addc_co_u32_e32 v1, vcc, 0, v1, vcc
	global_load_dwordx4 v[64:67], v[2:3], off offset:2048
	global_load_dwordx4 v[68:71], v[0:1], off offset:2048
	s_branch .LBB0_430
